# silu(gate) epilogue via v_rcp_f32 instead of IEEE division expansion (on top of fused attention bodies)
# speedup vs baseline: 1.0450x; 1.0059x over previous
; DI bf16x8 pack8(f32x8 v) { bf8v b = __builtin_convertvector(v, bf8v); return __builtin_bit_cast(bf16x8, b); }
;     __device__ __forceinline__ void operator()(const pg8::f32x4 (&acc)[2][2][4][2], const pg8::Unit& u, int wr, int wc, int fr, int fq) const {
;         const int ms = (u.pn & 7) >> 1, mixer = ((ms & 1) << 1) | (ms >> 1);
;         const int sec = u.pn >> 3, head = 4 * (u.pn & 1) + wc;
;         const int b = u.pm >> 5, blk = u.pm & 31, sbase = blk * 256 + wr * 64 + fr, bh = b * 8 + head;
;     ...
;         } else {
;             const int col = 512 * mixer + 256 * (u.pn & 1) + 64 * wc + 8 * fq;
; #pragma unroll
;             for (int ai = 0; ai < 2; ++ai)
; #pragma unroll
;                 for (int m = 0; m < 4; ++m) {
;                     const size_t row = (size_t)u.pm * 256 + 128 * ai + 64 * wr + 16 * m + fr;
; #pragma unroll
;                     for (int bj = 0; bj < 2; ++bj) {
;                         f32x8 t;
; #pragma unroll
;                         for (int n = 0; n < 2; ++n)
; #pragma unroll
;                             for (int e = 0; e < 4; ++e) { const float z = acc[ai][bj][m][n][e]; t[4 * n + e] = z / (1.0f + __expf(-z)); }
;                         *(bf16x8*)(G + row * DM + col + 32 * bj) = pack8(t);
;                     }
;                 }
.LBB0_134:
	s_bfe_u32 s1, s14, 0x10002
	s_and_b32 s2, s14, 2
	s_or_b32 s31, s1, s2
	s_and_b32 s1, s14, 1
	s_ashr_i32 s3, s0, 2
	s_lshl_b32 s2, s1, 2
	s_and_b32 s29, s0, 31
	s_and_b32 s3, s3, -8
	s_lshl_b32 s4, s29, 8
	s_or_b32 s2, s3, s2
	s_ashr_i32 s15, s14, 3
	s_add_i32 s4, s4, s58
	s_or_b32 s38, s2, s57
	v_or_b32_e32 v218, s4, v165
	s_cmp_gt_i32 s15, 1
	s_mov_b64 s[2:3], -1
	s_cbranch_scc0 .LBB0_141
	s_cmp_lg_u32 s15, 2
	s_cbranch_scc0 .LBB0_137
	v_mul_f32_e32 v2, 0xbfb8aa3b, v128
	v_exp_f32_e32 v132, v2
	v_mul_f32_e32 v2, 0xbfb8aa3b, v129
	v_exp_f32_e32 v133, v2
	s_lshl_b32 s2, s31, 9
	s_lshl_b32 s1, s1, 8
	s_or_b32 s1, s2, s1
	v_pk_add_f32 v[132:133], v[132:133], 1.0 op_sel_hi:[1,0]
	v_mul_f32_e32 v2, 0xbfb8aa3b, v130
	v_exp_f32_e32 v134, v2
	v_mul_f32_e32 v2, 0xbfb8aa3b, v131
	v_exp_f32_e32 v135, v2
	v_rcp_f32_e32 v138, v133
	s_nop 0
	v_mul_f32_e32 v138, v129, v138
	v_pk_add_f32 v[134:135], v[134:135], 1.0 op_sel_hi:[1,0]
	v_mul_f32_e32 v2, 0xbfb8aa3b, v124
	v_exp_f32_e32 v136, v2
	v_rcp_f32_e32 v133, v132
	s_nop 0
	v_mul_f32_e32 v132, v128, v133
	v_mul_f32_e32 v2, 0xbfb8aa3b, v125
	v_exp_f32_e32 v137, v2
	v_mul_f32_e32 v2, 0xbfb8aa3b, v126
	v_rcp_f32_e32 v133, v135
	s_nop 0
	v_mul_f32_e32 v133, v131, v133
	v_pk_add_f32 v[136:137], v[136:137], 1.0 op_sel_hi:[1,0]
	v_mul_f32_e32 v3, 0xbfb8aa3b, v127
	v_exp_f32_e32 v2, v2
	v_rcp_f32_e32 v135, v134
	s_nop 0
	v_mul_f32_e32 v139, v130, v135
	v_exp_f32_e32 v3, v3
	v_lshl_or_b32 v0, s57, 6, v174
	v_or_b32_e32 v0, s1, v0
	v_rcp_f32_e32 v134, v137
	s_nop 0
	v_mul_f32_e32 v134, v125, v134
	v_pk_add_f32 v[2:3], v[2:3], 1.0 op_sel_hi:[1,0]
	s_ashr_i32 s1, s0, 31
	s_lshl_b64 s[0:1], s[0:1], 20
	v_rcp_f32_e32 v135, v136
	s_nop 0
	v_mul_f32_e32 v136, v124, v135
	v_lshlrev_b32_e32 v0, 1, v0
	v_cvt_pk_bf16_f32 v134, v136, v134
	v_cvt_pk_bf16_f32 v133, v139, v133
	v_rcp_f32_e32 v135, v3
	s_nop 0
	v_mul_f32_e32 v3, v127, v135
	v_cvt_pk_bf16_f32 v132, v132, v138
	s_mov_b64 s[2:3], 0
	v_rcp_f32_e32 v135, v2
	s_nop 0
	v_mul_f32_e32 v2, v126, v135
	v_cvt_pk_bf16_f32 v135, v2, v3
	v_lshl_add_u64 v[2:3], v[212:213], 0, s[0:1]
	v_lshl_add_u64 v[2:3], v[2:3], 0, v[0:1]
	v_mul_f32_e32 v0, 0xbfb8aa3b, v120
	global_store_dwordx4 v[2:3], v[132:135], off
	s_nop 1
	v_exp_f32_e32 v134, v0
	v_mul_f32_e32 v0, 0xbfb8aa3b, v121
	v_exp_f32_e32 v135, v0
	v_mul_f32_e32 v0, 0xbfb8aa3b, v122
	v_exp_f32_e32 v136, v0
	v_mul_f32_e32 v0, 0xbfb8aa3b, v123
	v_exp_f32_e32 v137, v0
	v_mul_f32_e32 v0, 0xbfb8aa3b, v116
	v_exp_f32_e32 v138, v0
	v_mul_f32_e32 v0, 0xbfb8aa3b, v117
	v_exp_f32_e32 v139, v0
	v_mul_f32_e32 v0, 0xbfb8aa3b, v118
	v_exp_f32_e32 v132, v0
	v_mul_f32_e32 v0, 0xbfb8aa3b, v119
	v_pk_add_f32 v[134:135], v[134:135], 1.0 op_sel_hi:[1,0]
	v_exp_f32_e32 v133, v0
	v_pk_add_f32 v[136:137], v[136:137], 1.0 op_sel_hi:[1,0]
	v_pk_add_f32 v[138:139], v[138:139], 1.0 op_sel_hi:[1,0]
	v_pk_add_f32 v[132:133], v[132:133], 1.0 op_sel_hi:[1,0]
	v_rcp_f32_e32 v0, v135
	s_nop 0
	v_mul_f32_e32 v0, v121, v0
	s_nop 0
	v_rcp_f32_e32 v135, v134
	s_nop 0
	v_mul_f32_e32 v140, v120, v135
	s_nop 0
	v_rcp_f32_e32 v134, v137
	s_nop 0
	v_mul_f32_e32 v137, v123, v134
	s_nop 0
	v_rcp_f32_e32 v134, v136
	s_nop 0
	v_mul_f32_e32 v136, v122, v134
	s_nop 0
	v_rcp_f32_e32 v134, v139
	s_nop 0
	v_mul_f32_e32 v134, v117, v134
	s_nop 0
	v_rcp_f32_e32 v135, v138
	s_nop 0
	v_mul_f32_e32 v138, v116, v135
	v_cvt_pk_bf16_f32 v134, v138, v134
	v_rcp_f32_e32 v135, v133
	s_nop 0
	v_mul_f32_e32 v133, v119, v135
	s_nop 0
	v_rcp_f32_e32 v135, v132
	s_nop 0
	v_mul_f32_e32 v132, v118, v135
	v_cvt_pk_bf16_f32 v135, v132, v133
	v_cvt_pk_bf16_f32 v133, v136, v137
	v_cvt_pk_bf16_f32 v132, v140, v0
	v_mul_f32_e32 v0, 0xbfb8aa3b, v112
	global_store_dwordx4 v[2:3], v[132:135], off offset:64
	s_nop 1
	v_exp_f32_e32 v134, v0
	v_mul_f32_e32 v0, 0xbfb8aa3b, v113
	v_exp_f32_e32 v135, v0
	v_mul_f32_e32 v0, 0xbfb8aa3b, v114
	v_exp_f32_e32 v136, v0
	v_mul_f32_e32 v0, 0xbfb8aa3b, v115
	v_exp_f32_e32 v137, v0
	v_mul_f32_e32 v0, 0xbfb8aa3b, v108
	v_exp_f32_e32 v138, v0
	v_mul_f32_e32 v0, 0xbfb8aa3b, v109
	v_exp_f32_e32 v139, v0
	v_mul_f32_e32 v0, 0xbfb8aa3b, v110
	v_exp_f32_e32 v132, v0
	v_mul_f32_e32 v0, 0xbfb8aa3b, v111
	v_pk_add_f32 v[134:135], v[134:135], 1.0 op_sel_hi:[1,0]
	v_exp_f32_e32 v133, v0
	v_pk_add_f32 v[136:137], v[136:137], 1.0 op_sel_hi:[1,0]
	v_pk_add_f32 v[138:139], v[138:139], 1.0 op_sel_hi:[1,0]
	v_pk_add_f32 v[132:133], v[132:133], 1.0 op_sel_hi:[1,0]
	v_rcp_f32_e32 v0, v135
	s_nop 0
	v_mul_f32_e32 v0, v113, v0
	s_nop 0
	v_rcp_f32_e32 v135, v134
	s_nop 0
	v_mul_f32_e32 v134, v112, v135
	v_cvt_pk_bf16_f32 v134, v134, v0
	v_mul_f32_e32 v0, 0xbfb8aa3b, v104
	v_rcp_f32_e32 v135, v137
	s_nop 0
	v_mul_f32_e32 v135, v115, v135
	s_nop 0
	v_rcp_f32_e32 v137, v136
	s_nop 0
	v_mul_f32_e32 v140, v114, v137
	v_cvt_pk_bf16_f32 v135, v140, v135
	v_rcp_f32_e32 v136, v139
	s_nop 0
	v_mul_f32_e32 v136, v109, v136
	s_nop 0
	v_rcp_f32_e32 v137, v138
	s_nop 0
	v_mul_f32_e32 v138, v108, v137
	v_cvt_pk_bf16_f32 v136, v138, v136
	v_rcp_f32_e32 v137, v133
	s_nop 0
	v_mul_f32_e32 v133, v111, v137
	s_mov_b64 s[0:1], 0x10000
	v_rcp_f32_e32 v137, v132
	s_nop 0
	v_mul_f32_e32 v132, v110, v137
	v_cvt_pk_bf16_f32 v137, v132, v133
	v_lshl_add_u64 v[132:133], v[2:3], 0, s[0:1]
	s_mov_b32 s0, 0x10000
	v_add_co_u32_e32 v138, vcc, s0, v2
	s_nop 1
	v_addc_co_u32_e32 v139, vcc, 0, v3, vcc
	global_store_dwordx4 v[138:139], v[134:137], off
	s_nop 1
	v_exp_f32_e32 v136, v0
	v_mul_f32_e32 v0, 0xbfb8aa3b, v105
	v_exp_f32_e32 v137, v0
	v_mul_f32_e32 v0, 0xbfb8aa3b, v106
	v_exp_f32_e32 v138, v0
	v_mul_f32_e32 v0, 0xbfb8aa3b, v107
	v_exp_f32_e32 v139, v0
	v_mul_f32_e32 v0, 0xbfb8aa3b, v100
	v_exp_f32_e32 v140, v0
; DI bf16x8 pack8(f32x8 v) { bf8v b = __builtin_convertvector(v, bf8v); return __builtin_bit_cast(bf16x8, b); }
;     __device__ __forceinline__ void operator()(const pg8::f32x4 (&acc)[2][2][4][2], const pg8::Unit& u, int wr, int wc, int fr, int fq) const {
;     ...
;             for (int ai = 0; ai < 2; ++ai)
; #pragma unroll
;                 for (int m = 0; m < 4; ++m) {
;                     const size_t row = (size_t)u.pm * 256 + 128 * ai + 64 * wr + 16 * m + fr;
; #pragma unroll
;                     for (int bj = 0; bj < 2; ++bj) {
;                         f32x8 t;
; #pragma unroll
;                         for (int n = 0; n < 2; ++n)
; #pragma unroll
;                             for (int e = 0; e < 4; ++e) { const float z = acc[ai][bj][m][n][e]; t[4 * n + e] = z / (1.0f + __expf(-z)); }
;                         *(bf16x8*)(G + row * DM + col + 32 * bj) = pack8(t);
;                     }
;                 }
	v_mul_f32_e32 v0, 0xbfb8aa3b, v101
	v_exp_f32_e32 v141, v0
	v_mul_f32_e32 v0, 0xbfb8aa3b, v102
	v_exp_f32_e32 v134, v0
	v_mul_f32_e32 v0, 0xbfb8aa3b, v103
	v_pk_add_f32 v[136:137], v[136:137], 1.0 op_sel_hi:[1,0]
	v_exp_f32_e32 v135, v0
	v_pk_add_f32 v[138:139], v[138:139], 1.0 op_sel_hi:[1,0]
	v_pk_add_f32 v[140:141], v[140:141], 1.0 op_sel_hi:[1,0]
	v_pk_add_f32 v[134:135], v[134:135], 1.0 op_sel_hi:[1,0]
	v_rcp_f32_e32 v0, v137
	s_nop 0
	v_mul_f32_e32 v0, v105, v0
	s_nop 0
	v_rcp_f32_e32 v137, v136
	s_nop 0
	v_mul_f32_e32 v142, v104, v137
	s_nop 0
	v_rcp_f32_e32 v136, v139
	s_nop 0
	v_mul_f32_e32 v139, v107, v136
	s_nop 0
	v_rcp_f32_e32 v136, v138
	s_nop 0
	v_mul_f32_e32 v138, v106, v136
	s_nop 0
	v_rcp_f32_e32 v136, v141
	s_nop 0
	v_mul_f32_e32 v136, v101, v136
	s_nop 0
	v_rcp_f32_e32 v137, v140
	s_nop 0
	v_mul_f32_e32 v140, v100, v137
	v_cvt_pk_bf16_f32 v136, v140, v136
	v_rcp_f32_e32 v137, v135
	s_nop 0
	v_mul_f32_e32 v135, v103, v137
	s_nop 0
	v_rcp_f32_e32 v137, v134
	s_nop 0
	v_mul_f32_e32 v134, v102, v137
	v_cvt_pk_bf16_f32 v137, v134, v135
	v_cvt_pk_bf16_f32 v135, v138, v139
	v_cvt_pk_bf16_f32 v134, v142, v0
	v_mul_f32_e32 v0, 0xbfb8aa3b, v96
	global_store_dwordx4 v[132:133], v[134:137], off offset:64
	s_nop 1
	v_exp_f32_e32 v134, v0
	v_mul_f32_e32 v0, 0xbfb8aa3b, v97
	v_exp_f32_e32 v135, v0
	v_mul_f32_e32 v0, 0xbfb8aa3b, v98
	v_exp_f32_e32 v136, v0
	v_mul_f32_e32 v0, 0xbfb8aa3b, v99
	v_exp_f32_e32 v137, v0
	v_mul_f32_e32 v0, 0xbfb8aa3b, v92
	v_exp_f32_e32 v138, v0
	v_mul_f32_e32 v0, 0xbfb8aa3b, v93
	v_exp_f32_e32 v139, v0
	v_mul_f32_e32 v0, 0xbfb8aa3b, v94
	v_exp_f32_e32 v132, v0
	v_mul_f32_e32 v0, 0xbfb8aa3b, v95
	v_pk_add_f32 v[134:135], v[134:135], 1.0 op_sel_hi:[1,0]
	v_exp_f32_e32 v133, v0
	v_pk_add_f32 v[136:137], v[136:137], 1.0 op_sel_hi:[1,0]
	v_pk_add_f32 v[138:139], v[138:139], 1.0 op_sel_hi:[1,0]
	v_pk_add_f32 v[132:133], v[132:133], 1.0 op_sel_hi:[1,0]
	v_rcp_f32_e32 v0, v135
	s_nop 0
	v_mul_f32_e32 v0, v97, v0
	s_nop 0
	v_rcp_f32_e32 v135, v134
	s_nop 0
	v_mul_f32_e32 v134, v96, v135
	v_cvt_pk_bf16_f32 v134, v134, v0
	v_mul_f32_e32 v0, 0xbfb8aa3b, v88
	v_rcp_f32_e32 v135, v137
	s_nop 0
	v_mul_f32_e32 v135, v99, v135
	s_nop 0
	v_rcp_f32_e32 v137, v136
	s_nop 0
	v_mul_f32_e32 v140, v98, v137
	v_cvt_pk_bf16_f32 v135, v140, v135
	v_rcp_f32_e32 v136, v139
	s_nop 0
	v_mul_f32_e32 v136, v93, v136
	s_nop 0
	v_rcp_f32_e32 v137, v138
	s_nop 0
	v_mul_f32_e32 v138, v92, v137
	v_cvt_pk_bf16_f32 v136, v138, v136
	v_rcp_f32_e32 v137, v133
	s_nop 0
	v_mul_f32_e32 v133, v95, v137
	s_mov_b32 s0, 0x20000
	v_rcp_f32_e32 v137, v132
	s_nop 0
	v_mul_f32_e32 v132, v94, v137
	v_add_co_u32_e32 v138, vcc, s0, v2
	v_cvt_pk_bf16_f32 v137, v132, v133
	s_nop 0
	v_addc_co_u32_e32 v139, vcc, 0, v3, vcc
	global_store_dwordx4 v[138:139], v[134:137], off
	v_lshl_add_u64 v[132:133], v[2:3], 0, s[72:73]
	s_nop 0
	v_exp_f32_e32 v136, v0
	v_mul_f32_e32 v0, 0xbfb8aa3b, v89
	v_exp_f32_e32 v137, v0
	v_mul_f32_e32 v0, 0xbfb8aa3b, v90
	v_exp_f32_e32 v138, v0
	v_mul_f32_e32 v0, 0xbfb8aa3b, v91
	v_exp_f32_e32 v139, v0
	v_mul_f32_e32 v0, 0xbfb8aa3b, v84
	v_exp_f32_e32 v140, v0
	v_mul_f32_e32 v0, 0xbfb8aa3b, v85
	v_exp_f32_e32 v141, v0
	v_mul_f32_e32 v0, 0xbfb8aa3b, v86
	v_exp_f32_e32 v134, v0
	v_mul_f32_e32 v0, 0xbfb8aa3b, v87
	v_pk_add_f32 v[136:137], v[136:137], 1.0 op_sel_hi:[1,0]
	v_exp_f32_e32 v135, v0
	v_pk_add_f32 v[138:139], v[138:139], 1.0 op_sel_hi:[1,0]
	v_pk_add_f32 v[140:141], v[140:141], 1.0 op_sel_hi:[1,0]
	v_pk_add_f32 v[134:135], v[134:135], 1.0 op_sel_hi:[1,0]
	v_rcp_f32_e32 v0, v137
	s_nop 0
	v_mul_f32_e32 v0, v89, v0
	s_nop 0
	v_rcp_f32_e32 v137, v136
	s_nop 0
	v_mul_f32_e32 v142, v88, v137
	s_nop 0
	v_rcp_f32_e32 v136, v139
	s_nop 0
	v_mul_f32_e32 v139, v91, v136
	s_nop 0
	v_rcp_f32_e32 v136, v138
	s_nop 0
	v_mul_f32_e32 v138, v90, v136
	s_nop 0
	v_rcp_f32_e32 v136, v141
	s_nop 0
	v_mul_f32_e32 v136, v85, v136
	s_nop 0
	v_rcp_f32_e32 v137, v140
	s_nop 0
	v_mul_f32_e32 v140, v84, v137
	v_cvt_pk_bf16_f32 v136, v140, v136
	v_rcp_f32_e32 v137, v135
	s_nop 0
	v_mul_f32_e32 v135, v87, v137
	s_nop 0
	v_rcp_f32_e32 v137, v134
	s_nop 0
	v_mul_f32_e32 v134, v86, v137
	v_cvt_pk_bf16_f32 v137, v134, v135
	v_cvt_pk_bf16_f32 v135, v138, v139
	v_cvt_pk_bf16_f32 v134, v142, v0
	v_mul_f32_e32 v0, 0xbfb8aa3b, v80
	global_store_dwordx4 v[132:133], v[134:137], off offset:64
	s_nop 1
	v_exp_f32_e32 v134, v0
	v_mul_f32_e32 v0, 0xbfb8aa3b, v81
	v_exp_f32_e32 v135, v0
	v_mul_f32_e32 v0, 0xbfb8aa3b, v82
	v_exp_f32_e32 v136, v0
	v_mul_f32_e32 v0, 0xbfb8aa3b, v83
	v_exp_f32_e32 v137, v0
	v_mul_f32_e32 v0, 0xbfb8aa3b, v76
	v_exp_f32_e32 v138, v0
	v_mul_f32_e32 v0, 0xbfb8aa3b, v77
	v_exp_f32_e32 v139, v0
	v_mul_f32_e32 v0, 0xbfb8aa3b, v78
	v_exp_f32_e32 v132, v0
	v_mul_f32_e32 v0, 0xbfb8aa3b, v79
	v_pk_add_f32 v[134:135], v[134:135], 1.0 op_sel_hi:[1,0]
	v_exp_f32_e32 v133, v0
	v_pk_add_f32 v[136:137], v[136:137], 1.0 op_sel_hi:[1,0]
	v_pk_add_f32 v[138:139], v[138:139], 1.0 op_sel_hi:[1,0]
	v_pk_add_f32 v[132:133], v[132:133], 1.0 op_sel_hi:[1,0]
	v_rcp_f32_e32 v0, v135
	s_nop 0
	v_mul_f32_e32 v0, v81, v0
	s_nop 0
	v_rcp_f32_e32 v135, v134
	s_nop 0
	v_mul_f32_e32 v134, v80, v135
	v_cvt_pk_bf16_f32 v134, v134, v0
	v_mul_f32_e32 v0, 0xbfb8aa3b, v72
	v_rcp_f32_e32 v135, v137
	s_nop 0
	v_mul_f32_e32 v135, v83, v135
	s_nop 0
	v_rcp_f32_e32 v137, v136
	s_nop 0
	v_mul_f32_e32 v140, v82, v137
	v_cvt_pk_bf16_f32 v135, v140, v135
	v_rcp_f32_e32 v136, v139
	s_nop 0
	v_mul_f32_e32 v136, v77, v136
	s_nop 0
	v_rcp_f32_e32 v137, v138
	s_nop 0
	v_mul_f32_e32 v138, v76, v137
	v_cvt_pk_bf16_f32 v136, v138, v136
	v_rcp_f32_e32 v137, v133
	s_nop 0
	v_mul_f32_e32 v133, v79, v137
; DI bf16x8 pack8(f32x8 v) { bf8v b = __builtin_convertvector(v, bf8v); return __builtin_bit_cast(bf16x8, b); }
;     __device__ __forceinline__ void operator()(const pg8::f32x4 (&acc)[2][2][4][2], const pg8::Unit& u, int wr, int wc, int fr, int fq) const {
;     ...
;             const int col = 512 * mixer + 256 * (u.pn & 1) + 64 * wc + 8 * fq;
; #pragma unroll
;             for (int ai = 0; ai < 2; ++ai)
; #pragma unroll
;                 for (int m = 0; m < 4; ++m) {
;                     const size_t row = (size_t)u.pm * 256 + 128 * ai + 64 * wr + 16 * m + fr;
; #pragma unroll
;                     for (int bj = 0; bj < 2; ++bj) {
;                         f32x8 t;
; #pragma unroll
;                         for (int n = 0; n < 2; ++n)
; #pragma unroll
;                             for (int e = 0; e < 4; ++e) { const float z = acc[ai][bj][m][n][e]; t[4 * n + e] = z / (1.0f + __expf(-z)); }
;                         *(bf16x8*)(G + row * DM + col + 32 * bj) = pack8(t);
;                     }
;                 }
	s_mov_b64 s[0:1], 0x30000
	v_rcp_f32_e32 v137, v132
	s_nop 0
	v_mul_f32_e32 v132, v78, v137
	v_cvt_pk_bf16_f32 v137, v132, v133
	v_lshl_add_u64 v[132:133], v[2:3], 0, s[0:1]
	s_mov_b32 s0, 0x30000
	v_add_co_u32_e32 v138, vcc, s0, v2
	s_nop 1
	v_addc_co_u32_e32 v139, vcc, 0, v3, vcc
	global_store_dwordx4 v[138:139], v[134:137], off
	s_nop 1
	v_exp_f32_e32 v136, v0
	v_mul_f32_e32 v0, 0xbfb8aa3b, v73
	v_exp_f32_e32 v137, v0
	v_mul_f32_e32 v0, 0xbfb8aa3b, v74
	v_exp_f32_e32 v138, v0
	v_mul_f32_e32 v0, 0xbfb8aa3b, v75
	v_exp_f32_e32 v139, v0
	v_mul_f32_e32 v0, 0xbfb8aa3b, v68
	v_exp_f32_e32 v140, v0
	v_mul_f32_e32 v0, 0xbfb8aa3b, v69
	v_exp_f32_e32 v141, v0
	v_mul_f32_e32 v0, 0xbfb8aa3b, v70
	v_exp_f32_e32 v134, v0
	v_mul_f32_e32 v0, 0xbfb8aa3b, v71
	v_pk_add_f32 v[136:137], v[136:137], 1.0 op_sel_hi:[1,0]
	v_exp_f32_e32 v135, v0
	v_pk_add_f32 v[138:139], v[138:139], 1.0 op_sel_hi:[1,0]
	v_pk_add_f32 v[140:141], v[140:141], 1.0 op_sel_hi:[1,0]
	v_pk_add_f32 v[134:135], v[134:135], 1.0 op_sel_hi:[1,0]
	v_rcp_f32_e32 v0, v137
	s_nop 0
	v_mul_f32_e32 v0, v73, v0
	s_nop 0
	v_rcp_f32_e32 v137, v136
	s_nop 0
	v_mul_f32_e32 v142, v72, v137
	s_nop 0
	v_rcp_f32_e32 v136, v139
	s_nop 0
	v_mul_f32_e32 v139, v75, v136
	s_nop 0
	v_rcp_f32_e32 v136, v138
	s_nop 0
	v_mul_f32_e32 v138, v74, v136
	s_nop 0
	v_rcp_f32_e32 v136, v141
	s_nop 0
	v_mul_f32_e32 v136, v69, v136
	s_nop 0
	v_rcp_f32_e32 v137, v140
	s_nop 0
	v_mul_f32_e32 v140, v68, v137
	v_cvt_pk_bf16_f32 v136, v140, v136
	v_rcp_f32_e32 v137, v135
	s_nop 0
	v_mul_f32_e32 v135, v71, v137
	s_nop 0
	v_rcp_f32_e32 v137, v134
	s_nop 0
	v_mul_f32_e32 v134, v70, v137
	v_cvt_pk_bf16_f32 v137, v134, v135
	v_cvt_pk_bf16_f32 v135, v138, v139
	v_cvt_pk_bf16_f32 v134, v142, v0
	v_mul_f32_e32 v0, 0xbfb8aa3b, v64
	global_store_dwordx4 v[132:133], v[134:137], off offset:64
	s_nop 1
	v_exp_f32_e32 v134, v0
	v_mul_f32_e32 v0, 0xbfb8aa3b, v65
	v_exp_f32_e32 v135, v0
	v_mul_f32_e32 v0, 0xbfb8aa3b, v66
	v_exp_f32_e32 v136, v0
	v_mul_f32_e32 v0, 0xbfb8aa3b, v67
	v_exp_f32_e32 v137, v0
	v_mul_f32_e32 v0, 0xbfb8aa3b, v60
	v_exp_f32_e32 v138, v0
	v_mul_f32_e32 v0, 0xbfb8aa3b, v61
	v_exp_f32_e32 v139, v0
	v_mul_f32_e32 v0, 0xbfb8aa3b, v62
	v_exp_f32_e32 v132, v0
	v_mul_f32_e32 v0, 0xbfb8aa3b, v63
	v_pk_add_f32 v[134:135], v[134:135], 1.0 op_sel_hi:[1,0]
	v_exp_f32_e32 v133, v0
	v_pk_add_f32 v[136:137], v[136:137], 1.0 op_sel_hi:[1,0]
	v_pk_add_f32 v[138:139], v[138:139], 1.0 op_sel_hi:[1,0]
	v_pk_add_f32 v[132:133], v[132:133], 1.0 op_sel_hi:[1,0]
	v_rcp_f32_e32 v0, v135
	s_nop 0
	v_mul_f32_e32 v0, v65, v0
	s_nop 0
	v_rcp_f32_e32 v135, v134
	s_nop 0
	v_mul_f32_e32 v134, v64, v135
	v_cvt_pk_bf16_f32 v134, v134, v0
	v_mul_f32_e32 v0, 0xbfb8aa3b, v56
	v_rcp_f32_e32 v135, v137
	s_nop 0
	v_mul_f32_e32 v135, v67, v135
	s_nop 0
	v_rcp_f32_e32 v137, v136
	s_nop 0
	v_mul_f32_e32 v140, v66, v137
	v_cvt_pk_bf16_f32 v135, v140, v135
	v_rcp_f32_e32 v136, v139
	s_nop 0
	v_mul_f32_e32 v136, v61, v136
	s_nop 0
	v_rcp_f32_e32 v137, v138
	s_nop 0
	v_mul_f32_e32 v138, v60, v137
	v_cvt_pk_bf16_f32 v136, v138, v136
	v_rcp_f32_e32 v137, v133
	s_nop 0
	v_mul_f32_e32 v133, v63, v137
	s_mov_b64 s[0:1], 0x80000
	v_rcp_f32_e32 v137, v132
	s_nop 0
	v_mul_f32_e32 v132, v62, v137
	v_add_co_u32_e32 v138, vcc, s33, v2
	v_cvt_pk_bf16_f32 v137, v132, v133
	s_nop 0
	v_addc_co_u32_e32 v139, vcc, 0, v3, vcc
	global_store_dwordx4 v[138:139], v[134:137], off
	v_lshl_add_u64 v[132:133], v[2:3], 0, s[0:1]
	s_nop 0
	v_exp_f32_e32 v136, v0
	v_mul_f32_e32 v0, 0xbfb8aa3b, v57
	v_exp_f32_e32 v137, v0
	v_mul_f32_e32 v0, 0xbfb8aa3b, v58
	v_exp_f32_e32 v138, v0
	v_mul_f32_e32 v0, 0xbfb8aa3b, v59
	v_exp_f32_e32 v139, v0
	v_mul_f32_e32 v0, 0xbfb8aa3b, v52
	v_exp_f32_e32 v140, v0
	v_mul_f32_e32 v0, 0xbfb8aa3b, v53
	v_exp_f32_e32 v141, v0
	v_mul_f32_e32 v0, 0xbfb8aa3b, v54
	v_exp_f32_e32 v134, v0
	v_mul_f32_e32 v0, 0xbfb8aa3b, v55
	v_pk_add_f32 v[136:137], v[136:137], 1.0 op_sel_hi:[1,0]
	v_exp_f32_e32 v135, v0
	v_pk_add_f32 v[138:139], v[138:139], 1.0 op_sel_hi:[1,0]
	v_pk_add_f32 v[140:141], v[140:141], 1.0 op_sel_hi:[1,0]
	v_pk_add_f32 v[134:135], v[134:135], 1.0 op_sel_hi:[1,0]
	v_rcp_f32_e32 v0, v137
	s_nop 0
	v_mul_f32_e32 v0, v57, v0
	s_nop 0
	v_rcp_f32_e32 v137, v136
	s_nop 0
	v_mul_f32_e32 v142, v56, v137
	s_nop 0
	v_rcp_f32_e32 v136, v139
	s_nop 0
	v_mul_f32_e32 v139, v59, v136
	s_nop 0
	v_rcp_f32_e32 v136, v138
	s_nop 0
	v_mul_f32_e32 v138, v58, v136
	s_nop 0
	v_rcp_f32_e32 v136, v141
	s_nop 0
	v_mul_f32_e32 v136, v53, v136
	s_nop 0
	v_rcp_f32_e32 v137, v140
	s_nop 0
	v_mul_f32_e32 v140, v52, v137
	v_cvt_pk_bf16_f32 v136, v140, v136
	v_rcp_f32_e32 v137, v135
	s_nop 0
	v_mul_f32_e32 v135, v55, v137
	s_nop 0
	v_rcp_f32_e32 v137, v134
	s_nop 0
	v_mul_f32_e32 v134, v54, v137
	v_cvt_pk_bf16_f32 v137, v134, v135
	v_cvt_pk_bf16_f32 v135, v138, v139
	v_cvt_pk_bf16_f32 v134, v142, v0
	v_mul_f32_e32 v0, 0xbfb8aa3b, v48
	global_store_dwordx4 v[132:133], v[134:137], off offset:64
	s_nop 1
	v_exp_f32_e32 v134, v0
	v_mul_f32_e32 v0, 0xbfb8aa3b, v49
	v_exp_f32_e32 v135, v0
	v_mul_f32_e32 v0, 0xbfb8aa3b, v50
	v_exp_f32_e32 v136, v0
	v_mul_f32_e32 v0, 0xbfb8aa3b, v51
	v_exp_f32_e32 v137, v0
	v_mul_f32_e32 v0, 0xbfb8aa3b, v44
	v_exp_f32_e32 v138, v0
	v_mul_f32_e32 v0, 0xbfb8aa3b, v45
	v_exp_f32_e32 v139, v0
	v_mul_f32_e32 v0, 0xbfb8aa3b, v46
	v_exp_f32_e32 v132, v0
	v_mul_f32_e32 v0, 0xbfb8aa3b, v47
	v_pk_add_f32 v[134:135], v[134:135], 1.0 op_sel_hi:[1,0]
	v_exp_f32_e32 v133, v0
	v_pk_add_f32 v[136:137], v[136:137], 1.0 op_sel_hi:[1,0]
	v_pk_add_f32 v[138:139], v[138:139], 1.0 op_sel_hi:[1,0]
	v_pk_add_f32 v[132:133], v[132:133], 1.0 op_sel_hi:[1,0]
	v_rcp_f32_e32 v0, v135
	s_nop 0
; DI bf16x8 pack8(f32x8 v) { bf8v b = __builtin_convertvector(v, bf8v); return __builtin_bit_cast(bf16x8, b); }
;     __device__ __forceinline__ void operator()(const pg8::f32x4 (&acc)[2][2][4][2], const pg8::Unit& u, int wr, int wc, int fr, int fq) const {
;     ...
;             const int col = 512 * mixer + 256 * (u.pn & 1) + 64 * wc + 8 * fq;
; #pragma unroll
;             for (int ai = 0; ai < 2; ++ai)
; #pragma unroll
;                 for (int m = 0; m < 4; ++m) {
;                     const size_t row = (size_t)u.pm * 256 + 128 * ai + 64 * wr + 16 * m + fr;
; #pragma unroll
;                     for (int bj = 0; bj < 2; ++bj) {
;                         f32x8 t;
; #pragma unroll
;                         for (int n = 0; n < 2; ++n)
; #pragma unroll
;                             for (int e = 0; e < 4; ++e) { const float z = acc[ai][bj][m][n][e]; t[4 * n + e] = z / (1.0f + __expf(-z)); }
;                         *(bf16x8*)(G + row * DM + col + 32 * bj) = pack8(t);
;                     }
;                 }
	v_mul_f32_e32 v0, v49, v0
	s_nop 0
	v_rcp_f32_e32 v135, v134
	s_nop 0
	v_mul_f32_e32 v134, v48, v135
	v_cvt_pk_bf16_f32 v134, v134, v0
	v_mul_f32_e32 v0, 0xbfb8aa3b, v40
	v_rcp_f32_e32 v135, v137
	s_nop 0
	v_mul_f32_e32 v135, v51, v135
	s_nop 0
	v_rcp_f32_e32 v137, v136
	s_nop 0
	v_mul_f32_e32 v140, v50, v137
	v_cvt_pk_bf16_f32 v135, v140, v135
	v_rcp_f32_e32 v136, v139
	s_nop 0
	v_mul_f32_e32 v136, v45, v136
	s_nop 0
	v_rcp_f32_e32 v137, v138
	s_nop 0
	v_mul_f32_e32 v138, v44, v137
	v_cvt_pk_bf16_f32 v136, v138, v136
	v_rcp_f32_e32 v137, v133
	s_nop 0
	v_mul_f32_e32 v133, v47, v137
	s_mov_b64 s[0:1], 0x90000
	v_rcp_f32_e32 v137, v132
	s_nop 0
	v_mul_f32_e32 v132, v46, v137
	v_cvt_pk_bf16_f32 v137, v132, v133
	v_lshl_add_u64 v[132:133], v[2:3], 0, s[0:1]
	s_mov_b32 s0, 0x90000
	v_add_co_u32_e32 v138, vcc, s0, v2
	s_nop 1
	v_addc_co_u32_e32 v139, vcc, 0, v3, vcc
	global_store_dwordx4 v[138:139], v[134:137], off
	s_nop 1
	v_exp_f32_e32 v136, v0
	v_mul_f32_e32 v0, 0xbfb8aa3b, v41
	v_exp_f32_e32 v137, v0
	v_mul_f32_e32 v0, 0xbfb8aa3b, v42
	v_exp_f32_e32 v138, v0
	v_mul_f32_e32 v0, 0xbfb8aa3b, v43
	v_exp_f32_e32 v139, v0
	v_mul_f32_e32 v0, 0xbfb8aa3b, v36
	v_exp_f32_e32 v140, v0
	v_mul_f32_e32 v0, 0xbfb8aa3b, v37
	v_exp_f32_e32 v141, v0
	v_mul_f32_e32 v0, 0xbfb8aa3b, v38
	v_exp_f32_e32 v134, v0
	v_mul_f32_e32 v0, 0xbfb8aa3b, v39
	v_pk_add_f32 v[136:137], v[136:137], 1.0 op_sel_hi:[1,0]
	v_exp_f32_e32 v135, v0
	v_pk_add_f32 v[138:139], v[138:139], 1.0 op_sel_hi:[1,0]
	v_pk_add_f32 v[140:141], v[140:141], 1.0 op_sel_hi:[1,0]
	v_pk_add_f32 v[134:135], v[134:135], 1.0 op_sel_hi:[1,0]
	v_rcp_f32_e32 v0, v137
	s_nop 0
	v_mul_f32_e32 v0, v41, v0
	s_nop 0
	v_rcp_f32_e32 v137, v136
	s_nop 0
	v_mul_f32_e32 v142, v40, v137
	s_nop 0
	v_rcp_f32_e32 v136, v139
	s_nop 0
	v_mul_f32_e32 v139, v43, v136
	s_nop 0
	v_rcp_f32_e32 v136, v138
	s_nop 0
	v_mul_f32_e32 v138, v42, v136
	s_nop 0
	v_rcp_f32_e32 v136, v141
	s_nop 0
	v_mul_f32_e32 v136, v37, v136
	s_nop 0
	v_rcp_f32_e32 v137, v140
	s_nop 0
	v_mul_f32_e32 v140, v36, v137
	v_cvt_pk_bf16_f32 v136, v140, v136
	v_rcp_f32_e32 v137, v135
	s_nop 0
	v_mul_f32_e32 v135, v39, v137
	s_nop 0
	v_rcp_f32_e32 v137, v134
	s_nop 0
	v_mul_f32_e32 v134, v38, v137
	v_cvt_pk_bf16_f32 v137, v134, v135
	v_cvt_pk_bf16_f32 v135, v138, v139
	v_cvt_pk_bf16_f32 v134, v142, v0
	v_mul_f32_e32 v0, 0xbfb8aa3b, v32
	global_store_dwordx4 v[132:133], v[134:137], off offset:64
	s_nop 1
	v_exp_f32_e32 v134, v0
	v_mul_f32_e32 v0, 0xbfb8aa3b, v33
	v_exp_f32_e32 v135, v0
	v_mul_f32_e32 v0, 0xbfb8aa3b, v34
	v_exp_f32_e32 v136, v0
	v_mul_f32_e32 v0, 0xbfb8aa3b, v35
	v_exp_f32_e32 v137, v0
	v_mul_f32_e32 v0, 0xbfb8aa3b, v28
	v_exp_f32_e32 v138, v0
	v_mul_f32_e32 v0, 0xbfb8aa3b, v29
	v_exp_f32_e32 v139, v0
	v_mul_f32_e32 v0, 0xbfb8aa3b, v30
	v_exp_f32_e32 v132, v0
	v_mul_f32_e32 v0, 0xbfb8aa3b, v31
	v_pk_add_f32 v[134:135], v[134:135], 1.0 op_sel_hi:[1,0]
	v_exp_f32_e32 v133, v0
	v_pk_add_f32 v[136:137], v[136:137], 1.0 op_sel_hi:[1,0]
	v_pk_add_f32 v[138:139], v[138:139], 1.0 op_sel_hi:[1,0]
	v_pk_add_f32 v[132:133], v[132:133], 1.0 op_sel_hi:[1,0]
	v_rcp_f32_e32 v0, v135
	s_nop 0
	v_mul_f32_e32 v0, v33, v0
	s_nop 0
	v_rcp_f32_e32 v135, v134
	s_nop 0
	v_mul_f32_e32 v134, v32, v135
	v_cvt_pk_bf16_f32 v134, v134, v0
	v_mul_f32_e32 v0, 0xbfb8aa3b, v24
	v_rcp_f32_e32 v135, v137
	s_nop 0
	v_mul_f32_e32 v135, v35, v135
	s_nop 0
	v_rcp_f32_e32 v137, v136
	s_nop 0
	v_mul_f32_e32 v140, v34, v137
	v_cvt_pk_bf16_f32 v135, v140, v135
	v_rcp_f32_e32 v136, v139
	s_nop 0
	v_mul_f32_e32 v136, v29, v136
	s_nop 0
	v_rcp_f32_e32 v137, v138
	s_nop 0
	v_mul_f32_e32 v138, v28, v137
	v_cvt_pk_bf16_f32 v136, v138, v136
	v_rcp_f32_e32 v137, v133
	s_nop 0
	v_mul_f32_e32 v133, v31, v137
	s_mov_b64 s[0:1], 0xa0000
	v_rcp_f32_e32 v137, v132
	s_nop 0
	v_mul_f32_e32 v132, v30, v137
	v_cvt_pk_bf16_f32 v137, v132, v133
	v_lshl_add_u64 v[132:133], v[2:3], 0, s[0:1]
	s_mov_b32 s0, 0xa0000
	v_add_co_u32_e32 v138, vcc, s0, v2
	s_nop 1
	v_addc_co_u32_e32 v139, vcc, 0, v3, vcc
	global_store_dwordx4 v[138:139], v[134:137], off
	s_nop 1
	v_exp_f32_e32 v136, v0
	v_mul_f32_e32 v0, 0xbfb8aa3b, v25
	v_exp_f32_e32 v137, v0
	v_mul_f32_e32 v0, 0xbfb8aa3b, v26
	v_exp_f32_e32 v138, v0
	v_mul_f32_e32 v0, 0xbfb8aa3b, v27
	v_exp_f32_e32 v139, v0
	v_mul_f32_e32 v0, 0xbfb8aa3b, v20
; DI bf16x8 pack8(f32x8 v) { bf8v b = __builtin_convertvector(v, bf8v); return __builtin_bit_cast(bf16x8, b); }
;     __device__ __forceinline__ void operator()(const pg8::f32x4 (&acc)[2][2][4][2], const pg8::Unit& u, int wr, int wc, int fr, int fq) const {
;     ...
;             const int col = 512 * mixer + 256 * (u.pn & 1) + 64 * wc + 8 * fq;
; #pragma unroll
;             for (int ai = 0; ai < 2; ++ai)
; #pragma unroll
;                 for (int m = 0; m < 4; ++m) {
;                     const size_t row = (size_t)u.pm * 256 + 128 * ai + 64 * wr + 16 * m + fr;
; #pragma unroll
;                     for (int bj = 0; bj < 2; ++bj) {
;                         f32x8 t;
; #pragma unroll
;                         for (int n = 0; n < 2; ++n)
; #pragma unroll
;                             for (int e = 0; e < 4; ++e) { const float z = acc[ai][bj][m][n][e]; t[4 * n + e] = z / (1.0f + __expf(-z)); }
;                         *(bf16x8*)(G + row * DM + col + 32 * bj) = pack8(t);
;                     }
;                 }
	v_exp_f32_e32 v140, v0
	v_mul_f32_e32 v0, 0xbfb8aa3b, v21
	v_exp_f32_e32 v141, v0
	v_mul_f32_e32 v0, 0xbfb8aa3b, v22
	v_exp_f32_e32 v134, v0
	v_mul_f32_e32 v0, 0xbfb8aa3b, v23
	v_pk_add_f32 v[136:137], v[136:137], 1.0 op_sel_hi:[1,0]
	v_exp_f32_e32 v135, v0
	v_pk_add_f32 v[138:139], v[138:139], 1.0 op_sel_hi:[1,0]
	v_pk_add_f32 v[140:141], v[140:141], 1.0 op_sel_hi:[1,0]
	v_pk_add_f32 v[134:135], v[134:135], 1.0 op_sel_hi:[1,0]
	v_rcp_f32_e32 v0, v137
	s_nop 0
	v_mul_f32_e32 v0, v25, v0
	s_nop 0
	v_rcp_f32_e32 v137, v136
	s_nop 0
	v_mul_f32_e32 v142, v24, v137
	s_nop 0
	v_rcp_f32_e32 v136, v139
	s_nop 0
	v_mul_f32_e32 v139, v27, v136
	s_nop 0
	v_rcp_f32_e32 v136, v138
	s_nop 0
	v_mul_f32_e32 v138, v26, v136
	s_nop 0
	v_rcp_f32_e32 v136, v141
	s_nop 0
	v_mul_f32_e32 v136, v21, v136
	s_nop 0
	v_rcp_f32_e32 v137, v140
	s_nop 0
	v_mul_f32_e32 v140, v20, v137
	v_cvt_pk_bf16_f32 v136, v140, v136
	v_rcp_f32_e32 v137, v135
	s_nop 0
	v_mul_f32_e32 v135, v23, v137
	s_nop 0
	v_rcp_f32_e32 v137, v134
	s_nop 0
	v_mul_f32_e32 v134, v22, v137
	v_cvt_pk_bf16_f32 v137, v134, v135
	v_cvt_pk_bf16_f32 v135, v138, v139
	v_cvt_pk_bf16_f32 v134, v142, v0
	v_mul_f32_e32 v0, 0xbfb8aa3b, v16
	global_store_dwordx4 v[132:133], v[134:137], off offset:64
	s_nop 1
	v_exp_f32_e32 v134, v0
	v_mul_f32_e32 v0, 0xbfb8aa3b, v17
	v_exp_f32_e32 v135, v0
	v_mul_f32_e32 v0, 0xbfb8aa3b, v18
	v_exp_f32_e32 v136, v0
	v_mul_f32_e32 v0, 0xbfb8aa3b, v19
	v_exp_f32_e32 v137, v0
	v_mul_f32_e32 v0, 0xbfb8aa3b, v12
	v_exp_f32_e32 v138, v0
	v_mul_f32_e32 v0, 0xbfb8aa3b, v13
	v_exp_f32_e32 v139, v0
	v_mul_f32_e32 v0, 0xbfb8aa3b, v14
	v_exp_f32_e32 v132, v0
	v_mul_f32_e32 v0, 0xbfb8aa3b, v15
	v_pk_add_f32 v[134:135], v[134:135], 1.0 op_sel_hi:[1,0]
	v_exp_f32_e32 v133, v0
	v_pk_add_f32 v[136:137], v[136:137], 1.0 op_sel_hi:[1,0]
	v_pk_add_f32 v[138:139], v[138:139], 1.0 op_sel_hi:[1,0]
	v_pk_add_f32 v[132:133], v[132:133], 1.0 op_sel_hi:[1,0]
	v_rcp_f32_e32 v0, v135
	s_nop 0
	v_mul_f32_e32 v0, v17, v0
	s_nop 0
	v_rcp_f32_e32 v135, v134
	s_nop 0
	v_mul_f32_e32 v134, v16, v135
	v_cvt_pk_bf16_f32 v134, v134, v0
	v_mul_f32_e32 v0, 0xbfb8aa3b, v8
	v_rcp_f32_e32 v135, v137
	s_nop 0
	v_mul_f32_e32 v135, v19, v135
	s_nop 0
	v_rcp_f32_e32 v137, v136
	s_nop 0
	v_mul_f32_e32 v140, v18, v137
	v_cvt_pk_bf16_f32 v135, v140, v135
	v_rcp_f32_e32 v136, v139
	s_nop 0
	v_mul_f32_e32 v136, v13, v136
	s_nop 0
	v_rcp_f32_e32 v137, v138
	s_nop 0
	v_mul_f32_e32 v138, v12, v137
	v_cvt_pk_bf16_f32 v136, v138, v136
	v_rcp_f32_e32 v137, v133
	s_nop 0
	v_mul_f32_e32 v133, v15, v137
	s_mov_b64 s[0:1], 0xb0000
	v_rcp_f32_e32 v137, v132
	s_nop 0
	v_mul_f32_e32 v132, v14, v137
	v_cvt_pk_bf16_f32 v137, v132, v133
	v_lshl_add_u64 v[132:133], v[2:3], 0, s[0:1]
	s_mov_b32 s0, 0xb0000
	v_add_co_u32_e32 v2, vcc, s0, v2
	s_nop 1
	v_addc_co_u32_e32 v3, vcc, 0, v3, vcc
	global_store_dwordx4 v[2:3], v[134:137], off
	s_nop 1
	v_exp_f32_e32 v134, v0
	v_mul_f32_e32 v0, 0xbfb8aa3b, v9
	v_exp_f32_e32 v135, v0
	v_mul_f32_e32 v0, 0xbfb8aa3b, v10
	v_exp_f32_e32 v136, v0
	v_mul_f32_e32 v0, 0xbfb8aa3b, v11
	v_exp_f32_e32 v137, v0
	v_mul_f32_e32 v0, 0xbfb8aa3b, v4
	v_exp_f32_e32 v138, v0
	v_mul_f32_e32 v0, 0xbfb8aa3b, v5
	v_exp_f32_e32 v139, v0
	v_mul_f32_e32 v0, 0xbfb8aa3b, v6
	v_exp_f32_e32 v2, v0
	v_mul_f32_e32 v0, 0xbfb8aa3b, v7
	v_pk_add_f32 v[134:135], v[134:135], 1.0 op_sel_hi:[1,0]
	v_exp_f32_e32 v3, v0
	v_pk_add_f32 v[136:137], v[136:137], 1.0 op_sel_hi:[1,0]
	v_pk_add_f32 v[138:139], v[138:139], 1.0 op_sel_hi:[1,0]
	v_pk_add_f32 v[2:3], v[2:3], 1.0 op_sel_hi:[1,0]
	v_rcp_f32_e32 v0, v135
	s_nop 0
	v_mul_f32_e32 v0, v9, v0
	s_nop 0
	v_rcp_f32_e32 v135, v134
	s_nop 0
	v_mul_f32_e32 v134, v8, v135
	v_cvt_pk_bf16_f32 v134, v134, v0
	v_rcp_f32_e32 v135, v137
	s_nop 0
	v_mul_f32_e32 v135, v11, v135
	s_nop 0
	v_rcp_f32_e32 v137, v136
	s_nop 0
	v_mul_f32_e32 v140, v10, v137
	v_cvt_pk_bf16_f32 v135, v140, v135
	v_rcp_f32_e32 v136, v139
	s_nop 0
	v_mul_f32_e32 v136, v5, v136
	s_nop 0
	v_rcp_f32_e32 v137, v138
	s_nop 0
	v_mul_f32_e32 v138, v4, v137
	v_cvt_pk_bf16_f32 v136, v138, v136
	v_rcp_f32_e32 v137, v3
	s_nop 0
	v_mul_f32_e32 v3, v7, v137
	s_nop 0
	v_rcp_f32_e32 v137, v2
	s_nop 0
	v_mul_f32_e32 v2, v6, v137
	v_cvt_pk_bf16_f32 v137, v2, v3
	global_store_dwordx4 v[132:133], v[134:137], off offset:64
